# attention item prologue: bias-table load no longer waited before the Q / compressed-image loads are issued (table written at the first block sync)
# speedup vs baseline: 1.0051x; 1.0017x over previous
.LBB0_1077:
	s_or_b64 exec, exec, s[4:5]
	s_add_u32 s80, s76, s2
	s_addc_u32 s81, s77, s3
	s_ashr_i32 s17, s14, 6
	s_lshl_b32 s2, s93, 2
	s_lshl_b32 s3, s17, 5
	v_ashrrev_i32_e32 v1, 7, v129
	s_ashr_i32 s11, s14, 7
	s_and_b32 s2, s2, 12
	s_and_b32 s97, s3, 32
	s_lshl_b32 s3, s93, 9
	v_lshlrev_b32_e32 v0, 4, v0
	s_add_i32 s10, s11, s2
	s_and_b32 s87, s3, 0x3800
	v_add3_u32 v0, v1, s2, v0
	s_load_dwordx2 s[2:3], s[0:1], 0x10
	v_ashrrev_i32_e32 v1, 31, v0
	v_and_b32_e32 v18, 31, v129
	s_lshl_b32 s96, s79, 6
	v_or_b32_e32 v126, s97, v18
	s_waitcnt lgkmcnt(0)
	v_lshl_add_u64 v[0:1], v[0:1], 2, s[2:3]
	global_load_dword v235, v[0:1], off
	v_or_b32_e32 v125, s96, v126
	s_add_i32 s86, 0, 0x10000
	v_add_u32_e32 v32, s87, v125
	v_lshl_add_u32 v211, v129, 2, s86
	s_lshl_b32 s84, s10, 7
	v_bfe_u32 v124, v129, 5, 1
	s_ashr_i32 s85, s84, 31
	v_mbcnt_lo_u32_b32 v252, -1, 0
	v_mbcnt_hi_u32_b32 v252, -1, v252
	s_add_i32 s98, s96, s87
	v_and_or_b32 v228, v252, 31, s98
	v_or_b32_e32 v228, s97, v228
	v_mov_b32_e32 v229, 0
	v_lshlrev_b64 v[228:229], 12, v[228:229]
	v_lshl_add_u64 v[228:229], s[76:77], 0, v[228:229]
	v_lshl_add_u64 v[228:229], s[84:85], 1, v[228:229]
	v_lshrrev_b32_e32 v252, 2, v252
	v_and_b32_e32 v252, 8, v252
	v_mov_b32_e32 v253, 0
	v_lshl_add_u64 v[228:229], v[228:229], 0, v[252:253]
	s_mov_b64 s[98:99], 0x25e51000
	v_lshl_add_u64 v[228:229], v[228:229], 0, s[98:99]
	global_load_dwordx2 v[212:213], v[228:229], off
	global_load_dwordx2 v[214:215], v[228:229], off offset:16
	global_load_dwordx2 v[216:217], v[228:229], off offset:32
	global_load_dwordx2 v[218:219], v[228:229], off offset:48
	global_load_dwordx2 v[220:221], v[228:229], off offset:64
	global_load_dwordx2 v[222:223], v[228:229], off offset:80
	global_load_dwordx2 v[224:225], v[228:229], off offset:96
	global_load_dwordx2 v[226:227], v[228:229], off offset:112
	global_load_dwordx2 v[236:237], v[228:229], off offset:128
	global_load_dwordx2 v[238:239], v[228:229], off offset:144
	global_load_dwordx2 v[240:241], v[228:229], off offset:160
	global_load_dwordx2 v[242:243], v[228:229], off offset:176
	global_load_dwordx2 v[244:245], v[228:229], off offset:192
	global_load_dwordx2 v[246:247], v[228:229], off offset:208
	global_load_dwordx2 v[248:249], v[228:229], off offset:224
	global_load_dwordx2 v[250:251], v[228:229], off offset:240
	v_lshlrev_b32_e32 v2, 4, v124
	v_mov_b32_e32 v3, v33
	s_mov_b64 s[2:3], 0x21e51000
	s_and_b32 s92, s93, 31
	v_and_b32_e32 v19, 63, v129
	v_lshlrev_b32_e32 v20, 11, v124
	v_lshlrev_b32_e32 v16, 7, v124
	v_sub_u32_e32 v39, v125, v16
	v_max_i32_e32 v17, 31, v39
	v_max_i32_e32 v21, 47, v39
	v_subrev_u32_e32 v17, 31, v17
	v_subrev_u32_e32 v21, 47, v21
	v_min_u32_e32 v17, 0x7f, v17
	v_min_u32_e32 v21, 0x7f, v21
	v_lshlrev_b64 v[0:1], 12, v[32:33]
	v_lshl_add_u64 v[0:1], s[80:81], 0, v[0:1]
	v_lshl_add_u64 v[0:1], s[84:85], 1, v[0:1]
	v_lshl_add_u64 v[0:1], v[0:1], 0, v[2:3]
	v_lshl_add_u64 v[2:3], v[0:1], 0, s[2:3]
	s_mov_b32 s2, 0x21e51000
	v_add_co_u32_e32 v0, vcc, s2, v0
	s_lshl_b32 s2, s92, 15
	s_nop 0
	v_addc_co_u32_e32 v1, vcc, 0, v1, vcc
	global_load_dwordx4 v[130:133], v[0:1], off
	global_load_dwordx4 v[134:137], v[2:3], off offset:32
	global_load_dwordx4 v[138:141], v[2:3], off offset:64
	global_load_dwordx4 v[142:145], v[2:3], off offset:96
	global_load_dwordx4 v[146:149], v[2:3], off offset:128
	global_load_dwordx4 v[150:153], v[2:3], off offset:160
	global_load_dwordx4 v[154:157], v[2:3], off offset:192
	global_load_dwordx4 v[158:161], v[2:3], off offset:224
	s_add_u32 s4, s80, s2
	s_addc_u32 s5, s81, 0
	s_lshl_b32 s12, s17, 11
	s_ashr_i32 s13, s12, 31
	s_lshl_b64 s[2:3], s[12:13], 1
	s_add_u32 s2, s4, s2
	s_addc_u32 s3, s5, s3
	v_lshlrev_b32_e32 v0, 4, v19
	v_mov_b32_e32 v1, v33
	v_lshl_add_u64 v[0:1], s[2:3], 0, v[0:1]
	s_mov_b64 s[2:3], 0x4c359000
	v_lshl_add_u64 v[2:3], v[0:1], 0, s[2:3]
	s_lshl_b32 s2, s17, 12
	s_add_i32 s2, s2, 0
	s_mov_b32 m0, s2
	s_mov_b64 s[4:5], 0x4c359400
	global_load_lds_dwordx4 v[2:3], off
	v_lshl_add_u64 v[2:3], v[0:1], 0, s[4:5]
	s_add_i32 m0, s2, 0x400
	s_mov_b64 s[4:5], 0x4c359800
	global_load_lds_dwordx4 v[2:3], off
	v_lshl_add_u64 v[2:3], v[0:1], 0, s[4:5]
	s_add_i32 m0, s2, 0x800
	s_mov_b64 s[4:5], 0x4c359c00
	global_load_lds_dwordx4 v[2:3], off
	v_lshl_add_u64 v[2:3], v[0:1], 0, s[4:5]
	s_add_i32 m0, s2, 0xc00
	s_mov_b64 s[4:5], 0x4c459000
	global_load_lds_dwordx4 v[2:3], off
	v_lshl_add_u64 v[2:3], v[0:1], 0, s[4:5]
	s_add_i32 m0, s2, 0x8000
	s_mov_b64 s[4:5], 0x4c459400
	global_load_lds_dwordx4 v[2:3], off
	v_lshl_add_u64 v[2:3], v[0:1], 0, s[4:5]
	s_add_i32 m0, s2, 0x8400
	s_mov_b64 s[4:5], 0x4c459800
	global_load_lds_dwordx4 v[2:3], off
	v_lshl_add_u64 v[2:3], v[0:1], 0, s[4:5]
	s_add_i32 m0, s2, 0x8800
	s_mov_b64 s[4:5], 0x4c459c00
	global_load_lds_dwordx4 v[2:3], off
	v_lshl_add_u64 v[0:1], v[0:1], 0, s[4:5]
	s_add_i32 m0, s2, 0x8c00
	v_lshlrev_b32_e32 v2, 1, v129
	global_load_lds_dwordx4 v[0:1], off
	v_lshrrev_b32_e32 v1, 1, v129
	v_and_b32_e32 v0, 19, v129
	v_and_b32_e32 v1, 4, v1
	v_and_b32_e32 v2, 8, v2
	v_or3_b32 v0, v0, v1, v2
	v_lshl_add_u32 v127, v0, 4, 0
	s_waitcnt vmcnt(0) lgkmcnt(0)
	v_mul_f32_e32 v235, 0x3fb8aa3b, v235
	ds_write_b32 v211, v235
	s_waitcnt lgkmcnt(0)
	s_barrier
	v_add_u32_e32 v40, v127, v20
	ds_read_b128 v[0:3], v40
	ds_read_b128 v[22:25], v40 offset:4096
	s_waitcnt vmcnt(0) lgkmcnt(0)
	v_mfma_f32_32x32x16_bf16 v[0:15], v[0:3], v[130:133], 0
	s_and_b32 s2, s14, 0x3fffff80
	s_lshl_b32 s2, s2, 2
	s_add_i32 s86, s86, s2
	v_lshl_add_u32 v17, v17, 2, s86
	v_lshl_add_u32 v21, v21, 2, s86
	s_cmp_gt_u32 s79, 7
	s_cselect_b64 s[4:5], -1, 0
	v_mfma_f32_32x32x16_bf16 v[0:15], v[22:25], v[134:137], v[0:15]
	ds_read_b128 v[22:25], v40 offset:8192
	s_cmp_lt_u32 s79, 8
	s_waitcnt lgkmcnt(0)
	v_mfma_f32_32x32x16_bf16 v[0:15], v[22:25], v[138:141], v[0:15]
	ds_read_b128 v[22:25], v40 offset:12288
	s_waitcnt lgkmcnt(0)
	v_mfma_f32_32x32x16_bf16 v[0:15], v[22:25], v[142:145], v[0:15]
	ds_read_b128 v[22:25], v40 offset:16384
	s_waitcnt lgkmcnt(0)
	v_mfma_f32_32x32x16_bf16 v[0:15], v[22:25], v[146:149], v[0:15]
	ds_read_b128 v[22:25], v40 offset:20480
	s_waitcnt lgkmcnt(0)
	v_mfma_f32_32x32x16_bf16 v[0:15], v[22:25], v[150:153], v[0:15]
	ds_read_b128 v[22:25], v40 offset:24576
	s_waitcnt lgkmcnt(0)
	v_mfma_f32_32x32x16_bf16 v[0:15], v[22:25], v[154:157], v[0:15]
	ds_read_b128 v[22:25], v40 offset:28672
	s_waitcnt lgkmcnt(0)
	v_mfma_f32_32x32x16_bf16 v[0:15], v[22:25], v[158:161], v[0:15]
	v_max_i32_e32 v22, 63, v39
	v_subrev_u32_e32 v22, 63, v22
	v_min_u32_e32 v22, 0x7f, v22
	v_lshl_add_u32 v24, v22, 2, s86
	v_max_i32_e32 v22, 0x4f, v39
	v_add_u32_e32 v22, 0xffffffb1, v22
	v_min_u32_e32 v22, 0x7f, v22
	v_lshl_add_u32 v25, v22, 2, s86
	v_max_i32_e32 v22, 0x5f, v39
	v_add_u32_e32 v22, 0xffffffa1, v22
	v_min_u32_e32 v22, 0x7f, v22
	v_lshl_add_u32 v26, v22, 2, s86
	v_max_i32_e32 v22, 0x6f, v39
	v_add_u32_e32 v22, 0xffffff91, v22
	v_min_u32_e32 v22, 0x7f, v22
	v_lshl_add_u32 v27, v22, 2, s86
	v_max_i32_e32 v22, 0x7f, v39
	v_add_u32_e32 v22, 0xffffff81, v22
	v_min_u32_e32 v22, 0x7f, v22
	v_lshl_add_u32 v28, v22, 2, s86
	v_max_i32_e32 v22, 0x8f, v39
	v_add_u32_e32 v22, 0xffffff71, v22
	v_min_u32_e32 v22, 0x7f, v22
	v_lshl_add_u32 v29, v22, 2, s86
	v_max_i32_e32 v22, 0x11f, v39
	v_add_u32_e32 v22, 0xfffffee1, v22
	v_min_u32_e32 v22, 0x7f, v22
	v_lshl_add_u32 v30, v22, 2, s86
	v_max_i32_e32 v22, 0x12f, v39
	v_add_u32_e32 v22, 0xfffffed1, v22
	v_min_u32_e32 v22, 0x7f, v22
	v_lshl_add_u32 v31, v22, 2, s86
	v_max_i32_e32 v22, 0x13f, v39
	v_add_u32_e32 v22, 0xfffffec1, v22
	v_min_u32_e32 v22, 0x7f, v22
	v_lshl_add_u32 v34, v22, 2, s86
	v_max_i32_e32 v22, 0x14f, v39
	v_add_u32_e32 v22, 0xfffffeb1, v22
	v_min_u32_e32 v22, 0x7f, v22
	v_lshl_add_u32 v35, v22, 2, s86
	v_max_i32_e32 v22, 0x15f, v39
	v_add_u32_e32 v22, 0xfffffea1, v22
	v_min_u32_e32 v22, 0x7f, v22
	v_lshl_add_u32 v36, v22, 2, s86
	v_max_i32_e32 v22, 0x16f, v39
	v_add_u32_e32 v22, 0xfffffe91, v22
	v_min_u32_e32 v22, 0x7f, v22
	v_lshl_add_u32 v37, v22, 2, s86
	v_max_i32_e32 v22, 0x17f, v39
	v_add_u32_e32 v22, 0xfffffe81, v22
	v_min_u32_e32 v22, 0x7f, v22
	v_lshl_add_u32 v38, v22, 2, s86
	v_max_i32_e32 v22, 0x18f, v39
	v_add_u32_e32 v22, 0xfffffe71, v22
	v_min_u32_e32 v22, 0x7f, v22
	v_lshl_add_u32 v41, v22, 2, s86
	ds_read_b32 v22, v17
	ds_read_b32 v23, v21
	ds_read_b32 v24, v24
	ds_read_b32 v25, v25
	ds_read_b32 v26, v26
	ds_read_b32 v27, v27
	ds_read_b32 v21, v28
	ds_read_b32 v28, v29
	ds_read_b32 v42, v30
	ds_read_b32 v43, v31
	ds_read_b32 v44, v34
	ds_read_b32 v45, v35
	ds_read_b32 v46, v36
	ds_read_b32 v47, v37
	ds_read_b32 v48, v38
	ds_read_b32 v41, v41
	v_or_b32_e32 v29, 47, v16
	s_waitcnt lgkmcnt(14)
	v_or_b32_e32 v30, 31, v16
	v_pk_add_f32 v[0:1], v[0:1], v[22:23]
	v_cmp_ge_u32_e32 vcc, v125, v29
	v_or_b32_e32 v23, 0x4f, v16
	s_waitcnt lgkmcnt(13)
	s_waitcnt lgkmcnt(12)
	v_or_b32_e32 v29, 63, v16
	v_cndmask_b32_e32 v38, v231, v1, vcc
	v_cmp_ge_u32_e32 vcc, v125, v30
	s_waitcnt lgkmcnt(11)
	s_waitcnt lgkmcnt(10)
	s_waitcnt lgkmcnt(9)
	s_waitcnt lgkmcnt(8)
	s_waitcnt lgkmcnt(7)
	v_cndmask_b32_e32 v37, v231, v0, vcc
	v_pk_add_f32 v[0:1], v[2:3], v[24:25]
	v_cmp_ge_u32_e32 vcc, v125, v23
	v_max3_f32 v22, v37, s94, v38
	v_or_b32_e32 v3, 0x6f, v16
	v_cndmask_b32_e32 v36, v231, v1, vcc
	v_cmp_ge_u32_e32 vcc, v125, v29
	s_waitcnt lgkmcnt(6)
	s_waitcnt lgkmcnt(5)
	s_waitcnt lgkmcnt(4)
	s_waitcnt lgkmcnt(3)
	s_waitcnt lgkmcnt(2)
	v_cndmask_b32_e32 v35, v231, v0, vcc
	v_max3_f32 v2, v22, v35, v36
	v_or_b32_e32 v22, 0x5f, v16
	v_pk_add_f32 v[0:1], v[4:5], v[26:27]
	v_cmp_ge_u32_e32 vcc, v125, v3
	v_or_b32_e32 v3, 0x12f, v16
	v_or_b32_e32 v4, 0x11f, v16
	v_cndmask_b32_e32 v34, v231, v1, vcc
	v_cmp_ge_u32_e32 vcc, v125, v22
	v_or_b32_e32 v1, 0x7f, v16
	s_waitcnt lgkmcnt(1)
	s_waitcnt lgkmcnt(0)
	v_mov_b32_e32 v17, v16
	v_cndmask_b32_e32 v31, v231, v0, vcc
	v_max3_f32 v0, v2, v31, v34
	v_add_f32_e32 v2, v6, v21
	v_cmp_ge_u32_e32 vcc, v125, v1
	v_add_u32_e32 v1, 0x8f, v16
	s_nop 0
	v_cndmask_b32_e32 v29, v231, v2, vcc
	v_add_f32_e32 v2, v7, v28
	v_cmp_ge_u32_e32 vcc, v125, v1
	s_nop 1
	v_cndmask_b32_e32 v30, v231, v2, vcc
	v_max3_f32 v2, v0, v29, v30
	v_pk_add_f32 v[0:1], v[8:9], v[42:43]
	v_cmp_ge_u32_e32 vcc, v125, v3
	v_or_b32_e32 v3, 0x14f, v16
	s_nop 0
	v_cndmask_b32_e32 v28, v231, v1, vcc
	v_cmp_ge_u32_e32 vcc, v125, v4
	v_or_b32_e32 v4, 0x13f, v16
	s_nop 0
	v_cndmask_b32_e32 v27, v231, v0, vcc
	v_pk_add_f32 v[0:1], v[10:11], v[44:45]
	v_cmp_ge_u32_e32 vcc, v125, v3
	v_or_b32_e32 v3, 0x16f, v16
	v_max3_f32 v2, v2, v27, v28
	v_cndmask_b32_e32 v26, v231, v1, vcc
	v_cmp_ge_u32_e32 vcc, v125, v4
	v_or_b32_e32 v4, 0x15f, v16
	s_nop 0
	v_cndmask_b32_e32 v25, v231, v0, vcc
	v_pk_add_f32 v[0:1], v[12:13], v[46:47]
	v_cmp_ge_u32_e32 vcc, v125, v3
	v_max3_f32 v2, v2, v25, v26
	s_nop 0
	v_cndmask_b32_e32 v24, v231, v1, vcc
	v_cmp_ge_u32_e32 vcc, v125, v4
	v_or_b32_e32 v1, 0x17f, v16
	s_nop 0
	v_cndmask_b32_e32 v23, v231, v0, vcc
	v_max3_f32 v0, v2, v23, v24
	v_add_f32_e32 v2, v14, v48
	v_cmp_ge_u32_e32 vcc, v125, v1
	v_add_u32_e32 v1, 0x18f, v16
	s_nop 0
	v_cndmask_b32_e32 v21, v231, v2, vcc
	v_add_f32_e32 v2, v15, v41
	v_cmp_ge_u32_e32 vcc, v125, v1
	s_nop 1
	v_cndmask_b32_e32 v22, v231, v2, vcc
	v_max3_f32 v41, v0, v21, v22
	s_cbranch_scc1 .LBB0_1081
	ds_read_b128 v[0:3], v40 offset:512
	ds_read_b128 v[42:45], v40 offset:4608
	v_max_i32_e32 v46, 0x25f, v39
	v_max_i32_e32 v47, 0x26f, v39
	v_max_i32_e32 v48, 0x27f, v39
	v_max_i32_e32 v49, 0x28f, v39
	v_max_i32_e32 v50, 0x31f, v39
	v_max_i32_e32 v51, 0x32f, v39
	v_max_i32_e32 v52, 0x33f, v39
	s_waitcnt lgkmcnt(1)
	v_mfma_f32_32x32x16_bf16 v[0:15], v[0:3], v[130:133], 0
	v_max_i32_e32 v53, 0x34f, v39
	v_max_i32_e32 v54, 0x35f, v39
	v_max_i32_e32 v55, 0x36f, v39
	v_max_i32_e32 v56, 0x37f, v39
	v_add_u32_e32 v46, 0xfffffda1, v46
	v_add_u32_e32 v47, 0xfffffd91, v47
	v_add_u32_e32 v48, 0xfffffd81, v48
	s_waitcnt lgkmcnt(0)
	v_mfma_f32_32x32x16_bf16 v[0:15], v[42:45], v[134:137], v[0:15]
	ds_read_b128 v[42:45], v40 offset:8704
	v_add_u32_e32 v49, 0xfffffd71, v49
	v_add_u32_e32 v50, 0xfffffce1, v50
	v_add_u32_e32 v51, 0xfffffcd1, v51
	v_add_u32_e32 v52, 0xfffffcc1, v52
	v_add_u32_e32 v53, 0xfffffcb1, v53
	v_add_u32_e32 v54, 0xfffffca1, v54
	v_add_u32_e32 v55, 0xfffffc91, v55
	s_waitcnt lgkmcnt(0)
	v_mfma_f32_32x32x16_bf16 v[0:15], v[42:45], v[138:141], v[0:15]
	ds_read_b128 v[42:45], v40 offset:12800
	v_add_u32_e32 v56, 0xfffffc81, v56
	v_max_i32_e32 v57, 0x38f, v39
	v_min_u32_e32 v46, 0x7f, v46
	v_min_u32_e32 v47, 0x7f, v47
	v_min_u32_e32 v48, 0x7f, v48
	v_min_u32_e32 v49, 0x7f, v49
	s_waitcnt lgkmcnt(0)
	v_mfma_f32_32x32x16_bf16 v[0:15], v[42:45], v[142:145], v[0:15]
	ds_read_b128 v[42:45], v40 offset:16896
	v_min_u32_e32 v50, 0x7f, v50
	v_min_u32_e32 v51, 0x7f, v51
	v_min_u32_e32 v52, 0x7f, v52
	v_min_u32_e32 v53, 0x7f, v53
	v_min_u32_e32 v54, 0x7f, v54
	v_min_u32_e32 v55, 0x7f, v55
	s_waitcnt lgkmcnt(0)
	v_mfma_f32_32x32x16_bf16 v[0:15], v[42:45], v[146:149], v[0:15]
	ds_read_b128 v[42:45], v40 offset:20992
	v_min_u32_e32 v56, 0x7f, v56
	v_add_u32_e32 v57, 0xfffffc71, v57
	v_lshl_add_u32 v46, v46, 2, s86
	v_lshl_add_u32 v47, v47, 2, s86
	v_lshl_add_u32 v48, v48, 2, s86
	v_lshl_add_u32 v49, v49, 2, s86
	s_waitcnt lgkmcnt(0)
	v_mfma_f32_32x32x16_bf16 v[0:15], v[42:45], v[150:153], v[0:15]
	ds_read_b128 v[42:45], v40 offset:25088
	v_lshl_add_u32 v50, v50, 2, s86
	v_lshl_add_u32 v51, v51, 2, s86
	v_lshl_add_u32 v52, v52, 2, s86
	v_lshl_add_u32 v53, v53, 2, s86
	v_lshl_add_u32 v54, v54, 2, s86
	v_lshl_add_u32 v55, v55, 2, s86
	s_waitcnt lgkmcnt(0)
	v_mfma_f32_32x32x16_bf16 v[0:15], v[42:45], v[154:157], v[0:15]
	ds_read_b128 v[42:45], v40 offset:29184
	v_lshl_add_u32 v56, v56, 2, s86
	v_min_u32_e32 v57, 0x7f, v57
	v_lshl_add_u32 v57, v57, 2, s86
	s_waitcnt lgkmcnt(0)
	v_mfma_f32_32x32x16_bf16 v[0:15], v[42:45], v[158:161], v[0:15]
	v_max_i32_e32 v42, 0x21f, v39
	v_max_i32_e32 v43, 0x22f, v39
	v_max_i32_e32 v44, 0x23f, v39
	v_max_i32_e32 v45, 0x24f, v39
	v_add_u32_e32 v42, 0xfffffde1, v42
	v_add_u32_e32 v43, 0xfffffdd1, v43
	v_add_u32_e32 v44, 0xfffffdc1, v44
	v_add_u32_e32 v45, 0xfffffdb1, v45
	v_min_u32_e32 v42, 0x7f, v42
	v_min_u32_e32 v43, 0x7f, v43
	v_min_u32_e32 v44, 0x7f, v44
	v_min_u32_e32 v45, 0x7f, v45
	v_lshl_add_u32 v42, v42, 2, s86
	v_lshl_add_u32 v43, v43, 2, s86
	v_lshl_add_u32 v44, v44, 2, s86
	v_lshl_add_u32 v45, v45, 2, s86
	ds_read_b32 v42, v42
	ds_read_b32 v43, v43
	ds_read_b32 v44, v44
	ds_read_b32 v45, v45
	ds_read_b32 v46, v46
	ds_read_b32 v47, v47
	ds_read_b32 v58, v48
	ds_read_b32 v59, v49
	ds_read_b32 v48, v50
	ds_read_b32 v49, v51
	ds_read_b32 v50, v52
	ds_read_b32 v51, v53
	ds_read_b32 v52, v54
	ds_read_b32 v53, v55
	ds_read_b32 v54, v56
	ds_read_b32 v55, v57
	v_or_b32_e32 v56, 0x22f, v17
	s_waitcnt lgkmcnt(14)
	v_or_b32_e32 v57, 0x21f, v16
	v_pk_add_f32 v[0:1], v[0:1], v[42:43]
	v_cmp_ge_u32_e32 vcc, v125, v56
	v_or_b32_e32 v42, 0x24f, v17
	s_waitcnt lgkmcnt(13)
	s_waitcnt lgkmcnt(12)
	v_or_b32_e32 v43, 0x23f, v16
	v_cndmask_b32_e32 v67, v231, v1, vcc
	v_cmp_ge_u32_e32 vcc, v125, v57
	s_waitcnt lgkmcnt(11)
	s_waitcnt lgkmcnt(10)
	s_waitcnt lgkmcnt(9)
	s_waitcnt lgkmcnt(8)
	s_waitcnt lgkmcnt(7)
	v_cndmask_b32_e32 v66, v231, v0, vcc
	v_pk_add_f32 v[0:1], v[2:3], v[44:45]
	v_cmp_ge_u32_e32 vcc, v125, v42
	v_max3_f32 v41, v41, v66, v67
	v_or_b32_e32 v3, 0x26f, v17
	v_cndmask_b32_e32 v69, v231, v1, vcc
	v_cmp_ge_u32_e32 vcc, v125, v43
	s_waitcnt lgkmcnt(6)
	s_waitcnt lgkmcnt(5)
	s_waitcnt lgkmcnt(4)
	s_waitcnt lgkmcnt(3)
	s_waitcnt lgkmcnt(2)
	v_cndmask_b32_e32 v68, v231, v0, vcc
	v_max3_f32 v2, v41, v68, v69
	v_or_b32_e32 v41, 0x25f, v16
	v_pk_add_f32 v[0:1], v[4:5], v[46:47]
	v_cmp_ge_u32_e32 vcc, v125, v3
	v_or_b32_e32 v3, 0x32f, v17
	v_or_b32_e32 v4, 0x31f, v16
	v_cndmask_b32_e32 v71, v231, v1, vcc
	v_cmp_ge_u32_e32 vcc, v125, v41
	v_or_b32_e32 v1, 0x27f, v16
	s_waitcnt lgkmcnt(1)
	s_waitcnt lgkmcnt(0)
	v_cndmask_b32_e32 v70, v231, v0, vcc
	v_max3_f32 v0, v2, v70, v71
	v_add_f32_e32 v2, v6, v58
	v_cmp_ge_u32_e32 vcc, v125, v1
	v_add_u32_e32 v1, 0x28f, v16
	s_nop 0
	v_cndmask_b32_e32 v72, v231, v2, vcc
	v_add_f32_e32 v2, v7, v59
	v_cmp_ge_u32_e32 vcc, v125, v1
	s_nop 1
	v_cndmask_b32_e32 v73, v231, v2, vcc
	v_max3_f32 v2, v0, v72, v73
	v_pk_add_f32 v[0:1], v[8:9], v[48:49]
	v_cmp_ge_u32_e32 vcc, v125, v3
	v_or_b32_e32 v3, 0x34f, v17
	s_nop 0
	v_cndmask_b32_e32 v75, v231, v1, vcc
	v_cmp_ge_u32_e32 vcc, v125, v4
	v_or_b32_e32 v4, 0x33f, v16
	s_nop 0
	v_cndmask_b32_e32 v74, v231, v0, vcc
	v_pk_add_f32 v[0:1], v[10:11], v[50:51]
	v_cmp_ge_u32_e32 vcc, v125, v3
	v_or_b32_e32 v3, 0x36f, v17
	v_max3_f32 v2, v2, v74, v75
	v_cndmask_b32_e32 v77, v231, v1, vcc
	v_cmp_ge_u32_e32 vcc, v125, v4
	v_or_b32_e32 v4, 0x35f, v16
	s_nop 0
	v_cndmask_b32_e32 v76, v231, v0, vcc
	v_pk_add_f32 v[0:1], v[12:13], v[52:53]
	v_cmp_ge_u32_e32 vcc, v125, v3
	v_max3_f32 v2, v2, v76, v77
	s_nop 0
	v_cndmask_b32_e32 v79, v231, v1, vcc
	v_cmp_ge_u32_e32 vcc, v125, v4
	v_or_b32_e32 v1, 0x37f, v16
	s_nop 0
	v_cndmask_b32_e32 v78, v231, v0, vcc
	v_max3_f32 v0, v2, v78, v79
	v_add_f32_e32 v2, v14, v54
	v_cmp_ge_u32_e32 vcc, v125, v1
	v_add_u32_e32 v1, 0x38f, v16
	s_nop 0
	v_cndmask_b32_e32 v80, v231, v2, vcc
	v_add_f32_e32 v2, v15, v55
	v_cmp_ge_u32_e32 vcc, v125, v1
	s_nop 1
	v_cndmask_b32_e32 v81, v231, v2, vcc
	v_max3_f32 v41, v0, v80, v81
	s_cmp_gt_u32 s79, 15
	s_cselect_b64 s[6:7], -1, 0
	s_cmp_lt_u32 s79, 16
	s_cbranch_scc0 .LBB0_1082
